# v59 + P1 tail: fold units only on the workgroups with one P1a unit fewer (workgroups 0-9 no longer get a 4th unit)
# speedup vs baseline: 1.0137x; 1.0137x over previous
.LBB0_505:
	s_add_u32 s0, s94, 0x3bf00000
	s_addc_u32 s1, s95, 0
	v_writelane_b32 v253, s0, 10
	v_mov_b32_e32 v13, v0
	s_nop 0
	v_writelane_b32 v253, s1, 11
	s_add_i32 s1, s96, 0x76
	s_and_b32 s0, s1, 0xff
	s_cmpk_gt_u32 s0, 0x75
	v_readfirstlane_b32 s6, v13
	s_cbranch_scc1 .LBB0_521
	v_lshlrev_b32_e32 v2, 4, v13
	v_add_u32_e32 v3, 0x2000, v2
	v_ashrrev_i32_e32 v4, 31, v3
	v_lshrrev_b32_e32 v4, 22, v4
	v_add_u32_e32 v4, v3, v4
	v_ashrrev_i32_e32 v10, 10, v4
	v_mul_i32_i24_e32 v4, 0x400, v10
	v_sub_u32_e32 v3, v3, v4
	v_lshrrev_b32_e32 v4, 4, v3
	v_bitop3_b32 v3, v4, v3, 32 bitop3:0x6c
	v_ashrrev_i32_e32 v4, 31, v3
	v_lshrrev_b32_e32 v4, 26, v4
	v_add_u32_e32 v4, v3, v4
	v_lshlrev_b32_e32 v5, 3, v10
	v_ashrrev_i32_e32 v11, 6, v4
	v_and_b32_e32 v5, -16, v5
	v_add_u32_e32 v5, v11, v5
	s_waitcnt vmcnt(0)
	v_and_b32_e32 v6, 3, v11
	s_mov_b32 s2, 0x3fffe0
	v_lshrrev_b32_e32 v7, 2, v5
	v_lshlrev_b32_e32 v8, 1, v5
	v_and_b32_e32 v4, 0xc0, v4
	v_and_or_b32 v6, v5, s2, v6
	v_and_b32_e32 v7, 4, v7
	v_and_b32_e32 v8, 24, v8
	v_sub_u32_e32 v3, v3, v4
	v_mov_b32_e32 v4, 1
	v_or3_b32 v6, v6, v7, v8
	v_lshlrev_b32_e32 v7, 5, v10
	v_ashrrev_i16_sdwa v3, v4, sext(v3) dst_sel:DWORD dst_unused:UNUSED_PAD src0_sel:DWORD src1_sel:BYTE_0
	v_and_b32_e32 v7, 32, v7
	v_bfe_i32 v12, v3, 0, 16
	v_add_lshl_u32 v3, v7, v12, 1
	v_lshl_add_u32 v130, v6, 10, v3
	v_lshl_add_u32 v132, v5, 13, v3
	v_bfe_i32 v3, v13, 27, 1
	v_lshrrev_b32_e32 v3, 22, v3
	v_add_u32_e32 v3, v2, v3
	v_and_b32_e32 v3, 0xfffffc00, v3
	v_sub_u32_e32 v2, v2, v3
	v_lshrrev_b32_e32 v3, 4, v2
	v_ashrrev_i32_e32 v5, 31, v13
	v_bitop3_b32 v2, v3, v2, 32 bitop3:0x6c
	v_lshrrev_b32_e32 v5, 26, v5
	v_ashrrev_i32_e32 v3, 31, v2
	v_add_u32_e32 v5, v13, v5
	v_lshrrev_b32_e32 v3, 26, v3
	v_ashrrev_i32_e32 v15, 6, v5
	s_ashr_i32 s4, s6, 6
	v_add_u32_e32 v3, v2, v3
	v_lshlrev_b32_e32 v5, 3, v15
	s_ashr_i32 s7, s6, 8
	s_lshl_b32 s18, s4, 10
	s_lshr_b32 s47, s0, 4
	s_and_b32 s48, s1, 15
	v_ashrrev_i32_e32 v14, 6, v3
	v_and_b32_e32 v5, -16, v5
	s_add_u32 s1, s94, 0x8600000
	v_add_u32_e32 v5, v14, v5
	v_and_b32_e32 v6, 3, v14
	s_addc_u32 s8, s95, 0
	v_and_or_b32 v6, v5, s2, v6
	v_lshrrev_b32_e32 v7, 2, v5
	v_lshlrev_b32_e32 v8, 1, v5
	v_and_b32_e32 v3, 0xc0, v3
	s_lshl_b32 s2, s48, 21
	v_and_b32_e32 v7, 4, v7
	v_and_b32_e32 v8, 24, v8
	v_sub_u32_e32 v2, v2, v3
	s_add_u32 s5, s76, s2
	v_or3_b32 v6, v6, v7, v8
	v_lshlrev_b32_e32 v7, 5, v15
	v_ashrrev_i16_sdwa v2, v4, sext(v2) dst_sel:DWORD dst_unused:UNUSED_PAD src0_sel:DWORD src1_sel:BYTE_0
	s_addc_u32 s13, s77, 0
	s_lshl_b32 s2, s47, 18
	v_and_b32_e32 v7, 32, v7
	v_bfe_i32 v16, v2, 0, 16
	s_add_u32 s28, s1, s2
	v_add_lshl_u32 v2, v7, v16, 1
	s_addc_u32 s29, s8, 0
	s_add_i32 s9, s18, 0
	v_lshl_add_u32 v134, v6, 10, v2
	v_lshl_add_u32 v136, v5, 13, v2
	v_mov_b32_e32 v2, 0x7f7f7f7f
	s_add_i32 m0, s9, 0x10000
	s_lshl_b32 s2, s0, 5
	global_load_lds_dwordx4 v134, s[28:29]
	s_add_i32 m0, s9, 0x12000
	s_and_b32 s14, s2, 0xc00
	s_add_u32 s2, s28, 0x20000
	global_load_lds_dwordx4 v130, s[28:29]
	s_addc_u32 s3, s29, 0
	s_add_i32 m0, s9, 0x14000
	v_mov_b32_e32 v135, 0
	global_load_lds_dwordx4 v134, s[2:3]
	s_add_i32 m0, s9, 0x16000
	s_add_u32 s26, s5, s14
	s_addc_u32 s27, s13, 0
	s_add_i32 s13, s9, 0x2000
	global_load_lds_dwordx4 v130, s[2:3]
	s_mov_b32 m0, s9
	s_add_u32 s2, s26, 0x100000
	global_load_lds_dwordx4 v136, s[26:27]
	s_mov_b32 m0, s13
	s_addc_u32 s3, s27, 0
	s_add_i32 s14, s9, 0x4000
	global_load_lds_dwordx4 v132, s[26:27]
	s_mov_b32 m0, s14
	s_add_i32 s15, s9, 0x6000
	global_load_lds_dwordx4 v136, s[2:3]
	s_mov_b32 m0, s15
	v_mov_b32_e32 v131, v135
	global_load_lds_dwordx4 v132, s[2:3]
	v_mov_b32_e32 v137, v135
	v_mov_b32_e32 v133, v135
	s_cmp_eq_u32 s7, 1
	s_mov_b32 s33, 0
	v_lshl_add_u64 v[8:9], s[28:29], 0, v[134:135]
	v_lshl_add_u64 v[6:7], s[28:29], 0, v[130:131]
	v_lshl_add_u64 v[2:3], s[26:27], 0, v[136:137]
	s_cselect_b64 s[2:3], -1, 0
	s_cmp_lg_u32 s7, 1
	v_lshl_add_u64 v[4:5], s[26:27], 0, v[132:133]
	s_cbranch_scc1 .LBB0_508
	s_barrier

.LBB0_511:
	s_add_i32 s33, s33, 1
	s_mul_i32 s23, s33, 0x76
	s_add_i32 s23, s23, s0
	s_cmpk_lt_i32 s23, 0x80
	s_cselect_b64 s[24:25], -1, 0
	s_ashr_i32 s22, s23, 4
	s_and_b32 s46, s23, 15
	s_cmpk_gt_i32 s23, 0x7f
	s_cbranch_scc1 .LBB0_513
	s_ashr_i32 s18, s23, 5
	s_ashr_i32 s19, s18, 31
	s_lshl_b64 s[18:19], s[18:19], 10
	s_lshl_b32 s20, s46, 21
	s_add_u32 s20, s76, s20
	s_addc_u32 s21, s77, 0
	s_add_u32 s18, s20, s18
	s_addc_u32 s19, s21, s19
	s_ashr_i32 s23, s22, 31
	s_lshl_b64 s[20:21], s[22:23], 18
	s_add_u32 s20, s1, s20
	s_addc_u32 s21, s8, s21
